# speedup vs baseline: 1.0036x; 1.0036x over previous
.LBB0_38:
	s_add_u32 s2, s0, 0xffc50080
	s_addc_u32 s3, s1, -1
	s_add_i32 s96, 0, 0x10000
	s_cmp_eq_u32 s57, 12
	s_cselect_b32 s41, s53, s3
	s_cselect_b32 s40, s52, s2
	s_cselect_b32 s3, s22, s56
	s_cselect_b32 s2, s47, s49
	s_add_i32 s97, 0, 0x14000
	v_add_u32_e32 v102, s96, v241
	v_add_u32_e32 v142, s97, v241
	ds_read_b128 v[74:77], v102
	ds_read_b128 v[86:89], v102 offset:1024
	ds_read_b128 v[98:101], v102 offset:2048
	ds_read_b128 v[102:105], v102 offset:3072
	ds_read_b128 v[114:117], v142
	ds_read_b128 v[126:129], v142 offset:1024
	ds_read_b128 v[130:133], v142 offset:2048
	ds_read_b128 v[142:145], v142 offset:3072
	v_lshl_add_u64 v[194:195], s[0:1], 0, v[210:211]
	s_add_i32 m0, s60, 0xc000
	ds_read_b128 v[162:165], v242
	ds_read_b128 v[166:169], v242 offset:1024
	ds_read_b128 v[170:173], v242 offset:2048
	ds_read_b128 v[174:177], v242 offset:3072
	ds_read_b128 v[178:181], v242 offset:4096
	ds_read_b128 v[182:185], v242 offset:5120
	ds_read_b128 v[186:189], v242 offset:6144
	ds_read_b128 v[190:193], v242 offset:7168
	global_load_lds_dwordx4 v[194:195], off
	v_lshl_add_u64 v[194:195], v[194:195], 0, s[72:73]
	s_add_i32 m0, s60, 0xe000
	s_nop 0
	global_load_lds_dwordx4 v[194:195], off
	s_waitcnt vmcnt(8)
	s_waitcnt lgkmcnt(0)
	s_barrier
	s_setprio 1
	v_mfma_f32_16x16x32_bf16 v[158:161], v[74:77], v[162:165], v[158:161]
	v_mfma_f32_16x16x32_bf16 v[154:157], v[98:101], v[162:165], v[154:157]
	v_mfma_f32_16x16x32_bf16 v[134:137], v[98:101], v[170:173], v[134:137]
	v_mfma_f32_16x16x32_bf16 v[138:141], v[74:77], v[170:173], v[138:141]
	v_mfma_f32_16x16x32_bf16 v[110:113], v[74:77], v[178:181], v[110:113]
	v_mfma_f32_16x16x32_bf16 v[106:109], v[98:101], v[178:181], v[106:109]
	v_mfma_f32_16x16x32_bf16 v[78:81], v[98:101], v[186:189], v[78:81]
	v_mfma_f32_16x16x32_bf16 v[82:85], v[74:77], v[186:189], v[82:85]
	v_mfma_f32_16x16x32_bf16 v[158:161], v[86:89], v[166:169], v[158:161]
	v_mfma_f32_16x16x32_bf16 v[154:157], v[102:105], v[166:169], v[154:157]
	v_mfma_f32_16x16x32_bf16 v[134:137], v[102:105], v[174:177], v[134:137]
	v_mfma_f32_16x16x32_bf16 v[138:141], v[86:89], v[174:177], v[138:141]
	v_mfma_f32_16x16x32_bf16 v[110:113], v[86:89], v[182:185], v[110:113]
	v_mfma_f32_16x16x32_bf16 v[106:109], v[102:105], v[182:185], v[106:109]
	v_mfma_f32_16x16x32_bf16 v[78:81], v[102:105], v[190:193], v[78:81]
	v_mfma_f32_16x16x32_bf16 v[82:85], v[86:89], v[190:193], v[82:85]
	v_mfma_f32_16x16x32_bf16 v[150:153], v[114:117], v[162:165], v[150:153]
	v_mfma_f32_16x16x32_bf16 v[146:149], v[130:133], v[162:165], v[146:149]
	v_mfma_f32_16x16x32_bf16 v[118:121], v[130:133], v[170:173], v[118:121]
	v_mfma_f32_16x16x32_bf16 v[122:125], v[114:117], v[170:173], v[122:125]
	v_mfma_f32_16x16x32_bf16 v[94:97], v[114:117], v[178:181], v[94:97]
	v_mfma_f32_16x16x32_bf16 v[90:93], v[130:133], v[178:181], v[90:93]
	v_mfma_f32_16x16x32_bf16 v[66:69], v[130:133], v[186:189], v[66:69]
	v_mfma_f32_16x16x32_bf16 v[70:73], v[114:117], v[186:189], v[70:73]
	v_mfma_f32_16x16x32_bf16 v[150:153], v[126:129], v[166:169], v[150:153]
	v_mfma_f32_16x16x32_bf16 v[146:149], v[142:145], v[166:169], v[146:149]
	v_mfma_f32_16x16x32_bf16 v[118:121], v[142:145], v[174:177], v[118:121]
	v_mfma_f32_16x16x32_bf16 v[122:125], v[126:129], v[174:177], v[122:125]
	v_mfma_f32_16x16x32_bf16 v[94:97], v[126:129], v[182:185], v[94:97]
	v_mfma_f32_16x16x32_bf16 v[90:93], v[142:145], v[182:185], v[90:93]
	v_mfma_f32_16x16x32_bf16 v[66:69], v[142:145], v[190:193], v[66:69]
	v_mfma_f32_16x16x32_bf16 v[70:73], v[126:129], v[190:193], v[70:73]
	s_setprio 0
	s_barrier
	v_lshl_add_u64 v[194:195], s[2:3], 0, v[0:1]
	s_add_i32 s2, s96, s59
	s_mov_b32 m0, s2
	ds_read_b128 v[162:165], v242 offset:16384
	ds_read_b128 v[166:169], v242 offset:17408
	ds_read_b128 v[170:173], v242 offset:18432
	ds_read_b128 v[174:177], v242 offset:19456
	ds_read_b128 v[178:181], v242 offset:20480
	ds_read_b128 v[182:185], v242 offset:21504
	ds_read_b128 v[186:189], v242 offset:22528
	ds_read_b128 v[190:193], v242 offset:23552
	global_load_lds_dwordx4 v[194:195], off
	v_lshl_add_u64 v[196:197], v[194:195], 0, s[10:11]
	s_add_i32 m0, s2, 0x2000
	s_add_i32 s2, s97, s59
	global_load_lds_dwordx4 v[196:197], off
	v_lshl_add_u64 v[196:197], v[194:195], 0, s[26:27]
	s_mov_b32 m0, s2
	s_nop 0
	global_load_lds_dwordx4 v[196:197], off
	v_lshl_add_u64 v[196:197], v[194:195], 0, s[14:15]
	s_add_i32 m0, s2, 0x2000
	s_nop 0
	global_load_lds_dwordx4 v[196:197], off
	v_lshl_add_u64 v[196:197], s[40:41], 0, v[208:209]
	s_mov_b32 m0, s60
	v_lshl_add_u64 v[198:199], v[196:197], 0, s[72:73]
	global_load_lds_dwordx4 v[196:197], off
	s_mov_b32 m0, s61
	s_nop 0
	global_load_lds_dwordx4 v[198:199], off
	s_waitcnt vmcnt(8)
	s_waitcnt lgkmcnt(0)
	s_barrier
	s_setprio 1
	v_mfma_f32_16x16x32_bf16 v[62:65], v[74:77], v[162:165], v[62:65]
	v_mfma_f32_16x16x32_bf16 v[58:61], v[98:101], v[162:165], v[58:61]
	v_mfma_f32_16x16x32_bf16 v[42:45], v[98:101], v[170:173], v[42:45]
	v_mfma_f32_16x16x32_bf16 v[46:49], v[74:77], v[170:173], v[46:49]
	v_mfma_f32_16x16x32_bf16 v[30:33], v[74:77], v[178:181], v[30:33]
	v_mfma_f32_16x16x32_bf16 v[26:29], v[98:101], v[178:181], v[26:29]
	v_mfma_f32_16x16x32_bf16 v[10:13], v[98:101], v[186:189], v[10:13]
	v_mfma_f32_16x16x32_bf16 v[14:17], v[74:77], v[186:189], v[14:17]
	v_mfma_f32_16x16x32_bf16 v[62:65], v[86:89], v[166:169], v[62:65]
	v_mfma_f32_16x16x32_bf16 v[58:61], v[102:105], v[166:169], v[58:61]
	v_mfma_f32_16x16x32_bf16 v[42:45], v[102:105], v[174:177], v[42:45]
	v_mfma_f32_16x16x32_bf16 v[46:49], v[86:89], v[174:177], v[46:49]
	v_mfma_f32_16x16x32_bf16 v[30:33], v[86:89], v[182:185], v[30:33]
	v_mfma_f32_16x16x32_bf16 v[26:29], v[102:105], v[182:185], v[26:29]
	v_mfma_f32_16x16x32_bf16 v[10:13], v[102:105], v[190:193], v[10:13]
	v_mfma_f32_16x16x32_bf16 v[14:17], v[86:89], v[190:193], v[14:17]
	v_mfma_f32_16x16x32_bf16 v[54:57], v[114:117], v[162:165], v[54:57]
	v_mfma_f32_16x16x32_bf16 v[50:53], v[130:133], v[162:165], v[50:53]
	v_mfma_f32_16x16x32_bf16 v[34:37], v[130:133], v[170:173], v[34:37]
	v_mfma_f32_16x16x32_bf16 v[38:41], v[114:117], v[170:173], v[38:41]
	v_mfma_f32_16x16x32_bf16 v[22:25], v[114:117], v[178:181], v[22:25]
	v_mfma_f32_16x16x32_bf16 v[18:21], v[130:133], v[178:181], v[18:21]
	v_mfma_f32_16x16x32_bf16 v[2:5], v[130:133], v[186:189], v[2:5]
	v_mfma_f32_16x16x32_bf16 v[6:9], v[114:117], v[186:189], v[6:9]
	v_mfma_f32_16x16x32_bf16 v[54:57], v[126:129], v[166:169], v[54:57]
	v_mfma_f32_16x16x32_bf16 v[50:53], v[142:145], v[166:169], v[50:53]
	v_mfma_f32_16x16x32_bf16 v[34:37], v[142:145], v[174:177], v[34:37]
	v_mfma_f32_16x16x32_bf16 v[38:41], v[126:129], v[174:177], v[38:41]
	v_mfma_f32_16x16x32_bf16 v[22:25], v[126:129], v[182:185], v[22:25]
	v_mfma_f32_16x16x32_bf16 v[18:21], v[142:145], v[182:185], v[18:21]
	v_mfma_f32_16x16x32_bf16 v[2:5], v[142:145], v[190:193], v[2:5]
	v_mfma_f32_16x16x32_bf16 v[6:9], v[126:129], v[190:193], v[6:9]
	s_setprio 0
	s_barrier
	s_add_i32 s40, 0, 0x18000
	s_add_i32 s41, 0, 0x1c000
	v_add_u32_e32 v102, s40, v241
	v_add_u32_e32 v142, s41, v241
	ds_read_b128 v[74:77], v102
	ds_read_b128 v[86:89], v102 offset:1024
	ds_read_b128 v[98:101], v102 offset:2048
	ds_read_b128 v[102:105], v102 offset:3072
	ds_read_b128 v[114:117], v142
	ds_read_b128 v[126:129], v142 offset:1024
	ds_read_b128 v[130:133], v142 offset:2048
	ds_read_b128 v[142:145], v142 offset:3072
	s_mov_b64 s[2:3], 0x3b0000
	s_mov_b32 m0, s62
	v_lshl_add_u64 v[198:199], v[196:197], 0, s[2:3]
	s_mov_b64 s[2:3], 0x588000
	ds_read_b128 v[162:165], v242 offset:32768
	ds_read_b128 v[166:169], v242 offset:33792
	ds_read_b128 v[170:173], v242 offset:34816
	ds_read_b128 v[174:177], v242 offset:35840
	ds_read_b128 v[178:181], v242 offset:36864
	ds_read_b128 v[182:185], v242 offset:37888
	ds_read_b128 v[186:189], v242 offset:38912
	ds_read_b128 v[190:193], v242 offset:39936
	global_load_lds_dwordx4 v[198:199], off
	v_lshl_add_u64 v[198:199], v[196:197], 0, s[2:3]
	s_mov_b32 m0, s63
	s_nop 0
	global_load_lds_dwordx4 v[198:199], off
	s_waitcnt vmcnt(8)
	s_waitcnt lgkmcnt(0)
	s_barrier
	s_setprio 1
	v_mfma_f32_16x16x32_bf16 v[158:161], v[74:77], v[162:165], v[158:161]
	v_mfma_f32_16x16x32_bf16 v[154:157], v[98:101], v[162:165], v[154:157]
	v_mfma_f32_16x16x32_bf16 v[134:137], v[98:101], v[170:173], v[134:137]
	v_mfma_f32_16x16x32_bf16 v[138:141], v[74:77], v[170:173], v[138:141]
	v_mfma_f32_16x16x32_bf16 v[110:113], v[74:77], v[178:181], v[110:113]
	v_mfma_f32_16x16x32_bf16 v[106:109], v[98:101], v[178:181], v[106:109]
	v_mfma_f32_16x16x32_bf16 v[78:81], v[98:101], v[186:189], v[78:81]
	v_mfma_f32_16x16x32_bf16 v[82:85], v[74:77], v[186:189], v[82:85]
	v_mfma_f32_16x16x32_bf16 v[158:161], v[86:89], v[166:169], v[158:161]
	v_mfma_f32_16x16x32_bf16 v[154:157], v[102:105], v[166:169], v[154:157]
	v_mfma_f32_16x16x32_bf16 v[134:137], v[102:105], v[174:177], v[134:137]
	v_mfma_f32_16x16x32_bf16 v[138:141], v[86:89], v[174:177], v[138:141]
	v_mfma_f32_16x16x32_bf16 v[110:113], v[86:89], v[182:185], v[110:113]
	v_mfma_f32_16x16x32_bf16 v[106:109], v[102:105], v[182:185], v[106:109]
	v_mfma_f32_16x16x32_bf16 v[78:81], v[102:105], v[190:193], v[78:81]
	v_mfma_f32_16x16x32_bf16 v[82:85], v[86:89], v[190:193], v[82:85]
	v_mfma_f32_16x16x32_bf16 v[150:153], v[114:117], v[162:165], v[150:153]
	v_mfma_f32_16x16x32_bf16 v[146:149], v[130:133], v[162:165], v[146:149]
	v_mfma_f32_16x16x32_bf16 v[118:121], v[130:133], v[170:173], v[118:121]
	v_mfma_f32_16x16x32_bf16 v[122:125], v[114:117], v[170:173], v[122:125]
	v_mfma_f32_16x16x32_bf16 v[94:97], v[114:117], v[178:181], v[94:97]
	v_mfma_f32_16x16x32_bf16 v[90:93], v[130:133], v[178:181], v[90:93]
	v_mfma_f32_16x16x32_bf16 v[66:69], v[130:133], v[186:189], v[66:69]
	v_mfma_f32_16x16x32_bf16 v[70:73], v[114:117], v[186:189], v[70:73]
	v_mfma_f32_16x16x32_bf16 v[150:153], v[126:129], v[166:169], v[150:153]
	v_mfma_f32_16x16x32_bf16 v[146:149], v[142:145], v[166:169], v[146:149]
	v_mfma_f32_16x16x32_bf16 v[118:121], v[142:145], v[174:177], v[118:121]
	v_mfma_f32_16x16x32_bf16 v[122:125], v[126:129], v[174:177], v[122:125]
	v_mfma_f32_16x16x32_bf16 v[94:97], v[126:129], v[182:185], v[94:97]
	v_mfma_f32_16x16x32_bf16 v[90:93], v[142:145], v[182:185], v[90:93]
	v_mfma_f32_16x16x32_bf16 v[66:69], v[142:145], v[190:193], v[66:69]
	v_mfma_f32_16x16x32_bf16 v[70:73], v[126:129], v[190:193], v[70:73]
	s_setprio 0
	s_barrier
	s_add_i32 s2, s40, s59
	v_lshl_add_u64 v[198:199], v[194:195], 0, s[30:31]
	s_mov_b32 m0, s2
	ds_read_b128 v[162:165], v242 offset:49152
	ds_read_b128 v[166:169], v242 offset:50176
	ds_read_b128 v[170:173], v242 offset:51200
	ds_read_b128 v[174:177], v242 offset:52224
	ds_read_b128 v[178:181], v242 offset:53248
	ds_read_b128 v[182:185], v242 offset:54272
	ds_read_b128 v[186:189], v242 offset:55296
	ds_read_b128 v[190:193], v242 offset:56320
	global_load_lds_dwordx4 v[198:199], off
	v_lshl_add_u64 v[198:199], v[194:195], 0, s[24:25]
	s_add_i32 m0, s2, 0x2000
	s_add_i32 s2, s41, s59
	global_load_lds_dwordx4 v[198:199], off
	v_lshl_add_u64 v[198:199], v[194:195], 0, s[50:51]
	s_mov_b32 m0, s2
	v_lshl_add_u64 v[194:195], v[194:195], 0, s[4:5]
	global_load_lds_dwordx4 v[198:199], off
	s_add_i32 m0, s2, 0x2000
	s_mov_b64 s[2:3], 0x1d8080
	global_load_lds_dwordx4 v[194:195], off
	v_lshl_add_u64 v[194:195], v[196:197], 0, s[30:31]
	s_mov_b32 m0, s66
	s_nop 0
	global_load_lds_dwordx4 v[194:195], off
	v_lshl_add_u64 v[194:195], v[196:197], 0, s[2:3]
	s_mov_b32 m0, s67
	s_nop 0
	global_load_lds_dwordx4 v[194:195], off
	s_waitcnt vmcnt(8)
	s_waitcnt lgkmcnt(0)
	s_barrier
	s_setprio 1
	v_mfma_f32_16x16x32_bf16 v[62:65], v[74:77], v[162:165], v[62:65]
	v_mfma_f32_16x16x32_bf16 v[58:61], v[98:101], v[162:165], v[58:61]
	v_mfma_f32_16x16x32_bf16 v[42:45], v[98:101], v[170:173], v[42:45]
	v_mfma_f32_16x16x32_bf16 v[46:49], v[74:77], v[170:173], v[46:49]
	v_mfma_f32_16x16x32_bf16 v[30:33], v[74:77], v[178:181], v[30:33]
	v_mfma_f32_16x16x32_bf16 v[26:29], v[98:101], v[178:181], v[26:29]
	v_mfma_f32_16x16x32_bf16 v[10:13], v[98:101], v[186:189], v[10:13]
	v_mfma_f32_16x16x32_bf16 v[14:17], v[74:77], v[186:189], v[14:17]
	v_mfma_f32_16x16x32_bf16 v[62:65], v[86:89], v[166:169], v[62:65]
	v_mfma_f32_16x16x32_bf16 v[58:61], v[102:105], v[166:169], v[58:61]
	v_mfma_f32_16x16x32_bf16 v[42:45], v[102:105], v[174:177], v[42:45]
	v_mfma_f32_16x16x32_bf16 v[46:49], v[86:89], v[174:177], v[46:49]
	v_mfma_f32_16x16x32_bf16 v[30:33], v[86:89], v[182:185], v[30:33]
	v_mfma_f32_16x16x32_bf16 v[26:29], v[102:105], v[182:185], v[26:29]
	v_mfma_f32_16x16x32_bf16 v[10:13], v[102:105], v[190:193], v[10:13]
	v_mfma_f32_16x16x32_bf16 v[14:17], v[86:89], v[190:193], v[14:17]
	v_mfma_f32_16x16x32_bf16 v[54:57], v[114:117], v[162:165], v[54:57]
	v_mfma_f32_16x16x32_bf16 v[50:53], v[130:133], v[162:165], v[50:53]
	v_mfma_f32_16x16x32_bf16 v[34:37], v[130:133], v[170:173], v[34:37]
	v_mfma_f32_16x16x32_bf16 v[38:41], v[114:117], v[170:173], v[38:41]
	v_mfma_f32_16x16x32_bf16 v[22:25], v[114:117], v[178:181], v[22:25]
	v_mfma_f32_16x16x32_bf16 v[18:21], v[130:133], v[178:181], v[18:21]
	v_mfma_f32_16x16x32_bf16 v[2:5], v[130:133], v[186:189], v[2:5]
	v_mfma_f32_16x16x32_bf16 v[6:9], v[114:117], v[186:189], v[6:9]
	v_mfma_f32_16x16x32_bf16 v[54:57], v[126:129], v[166:169], v[54:57]
	v_mfma_f32_16x16x32_bf16 v[50:53], v[142:145], v[166:169], v[50:53]
	v_mfma_f32_16x16x32_bf16 v[34:37], v[142:145], v[174:177], v[34:37]
	v_mfma_f32_16x16x32_bf16 v[38:41], v[126:129], v[174:177], v[38:41]
	v_mfma_f32_16x16x32_bf16 v[22:25], v[126:129], v[182:185], v[22:25]
	v_mfma_f32_16x16x32_bf16 v[18:21], v[142:145], v[182:185], v[18:21]
	v_mfma_f32_16x16x32_bf16 v[2:5], v[142:145], v[190:193], v[2:5]
	v_mfma_f32_16x16x32_bf16 v[6:9], v[126:129], v[190:193], v[6:9]
	s_setprio 0
	s_barrier
	s_add_i32 s57, s57, 2
	s_add_u32 s0, s0, 0x100
	s_addc_u32 s1, s1, 0
	s_add_u32 s49, s49, 0x100
	s_addc_u32 s56, s56, 0
	s_cmp_gt_u32 s57, 13
	s_cbranch_scc0 .LBB0_38
	s_and_b64 vcc, exec, s[44:45]
	s_cbranch_vccz .LBB0_41
	s_barrier

.LBB0_406:
	s_add_u32 s2, s58, 0xfff80080
	s_addc_u32 s3, s59, -1
	s_add_i32 s67, 0, 0x10000
	s_cmp_eq_u32 s66, 28
	s_cselect_b32 s61, s53, s3
	s_cselect_b32 s60, s62, s2
	s_cselect_b32 s3, s49, s65
	s_cselect_b32 s2, s63, s64
	s_add_i32 vcc_lo, 0, 0x14000
	v_add_u32_e32 v142, s67, v224
	v_add_u32_e32 v158, vcc_lo, v224
	ds_read_b128 v[126:129], v142
	ds_read_b128 v[134:137], v142 offset:1024
	ds_read_b128 v[138:141], v142 offset:2048
	ds_read_b128 v[142:145], v142 offset:3072
	ds_read_b128 v[146:149], v158
	ds_read_b128 v[150:153], v158 offset:1024
	ds_read_b128 v[154:157], v158 offset:2048
	ds_read_b128 v[158:161], v158 offset:3072
	v_lshl_add_u64 v[196:197], s[58:59], 0, v[190:191]
	s_add_i32 m0, s95, 0xc000
	ds_read_b128 v[162:165], v225
	ds_read_b128 v[166:169], v225 offset:1024
	ds_read_b128 v[170:173], v225 offset:2048
	ds_read_b128 v[174:177], v225 offset:3072
	ds_read_b128 v[178:181], v225 offset:4096
	ds_read_b128 v[182:185], v225 offset:5120
	ds_read_b128 v[186:189], v225 offset:6144
	ds_read_b128 v[192:195], v225 offset:7168
	global_load_lds_dwordx4 v[196:197], off
	v_lshl_add_u64 v[196:197], v[196:197], 0, s[26:27]
	s_add_i32 m0, s95, 0xe000
	s_nop 0
	global_load_lds_dwordx4 v[196:197], off
	s_waitcnt vmcnt(8)
	s_waitcnt lgkmcnt(0)
	s_barrier
	s_setprio 1
	v_mfma_f32_16x16x32_bf16 v[130:133], v[126:129], v[162:165], v[130:133]
	v_mfma_f32_16x16x32_bf16 v[122:125], v[138:141], v[162:165], v[122:125]
	v_mfma_f32_16x16x32_bf16 v[106:109], v[138:141], v[170:173], v[106:109]
	v_mfma_f32_16x16x32_bf16 v[110:113], v[126:129], v[170:173], v[110:113]
	v_mfma_f32_16x16x32_bf16 v[94:97], v[126:129], v[178:181], v[94:97]
	v_mfma_f32_16x16x32_bf16 v[90:93], v[138:141], v[178:181], v[90:93]
	v_mfma_f32_16x16x32_bf16 v[74:77], v[138:141], v[186:189], v[74:77]
	v_mfma_f32_16x16x32_bf16 v[78:81], v[126:129], v[186:189], v[78:81]
	v_mfma_f32_16x16x32_bf16 v[130:133], v[134:137], v[166:169], v[130:133]
	v_mfma_f32_16x16x32_bf16 v[122:125], v[142:145], v[166:169], v[122:125]
	v_mfma_f32_16x16x32_bf16 v[106:109], v[142:145], v[174:177], v[106:109]
	v_mfma_f32_16x16x32_bf16 v[110:113], v[134:137], v[174:177], v[110:113]
	v_mfma_f32_16x16x32_bf16 v[94:97], v[134:137], v[182:185], v[94:97]
	v_mfma_f32_16x16x32_bf16 v[90:93], v[142:145], v[182:185], v[90:93]
	v_mfma_f32_16x16x32_bf16 v[74:77], v[142:145], v[192:195], v[74:77]
	v_mfma_f32_16x16x32_bf16 v[78:81], v[134:137], v[192:195], v[78:81]
	v_mfma_f32_16x16x32_bf16 v[118:121], v[146:149], v[162:165], v[118:121]
	v_mfma_f32_16x16x32_bf16 v[114:117], v[154:157], v[162:165], v[114:117]
	v_mfma_f32_16x16x32_bf16 v[98:101], v[154:157], v[170:173], v[98:101]
	v_mfma_f32_16x16x32_bf16 v[102:105], v[146:149], v[170:173], v[102:105]
	v_mfma_f32_16x16x32_bf16 v[86:89], v[146:149], v[178:181], v[86:89]
	v_mfma_f32_16x16x32_bf16 v[82:85], v[154:157], v[178:181], v[82:85]
	v_mfma_f32_16x16x32_bf16 v[66:69], v[154:157], v[186:189], v[66:69]
	v_mfma_f32_16x16x32_bf16 v[70:73], v[146:149], v[186:189], v[70:73]
	v_mfma_f32_16x16x32_bf16 v[118:121], v[150:153], v[166:169], v[118:121]
	v_mfma_f32_16x16x32_bf16 v[114:117], v[158:161], v[166:169], v[114:117]
	v_mfma_f32_16x16x32_bf16 v[98:101], v[158:161], v[174:177], v[98:101]
	v_mfma_f32_16x16x32_bf16 v[102:105], v[150:153], v[174:177], v[102:105]
	v_mfma_f32_16x16x32_bf16 v[86:89], v[150:153], v[182:185], v[86:89]
	v_mfma_f32_16x16x32_bf16 v[82:85], v[158:161], v[182:185], v[82:85]
	v_mfma_f32_16x16x32_bf16 v[66:69], v[158:161], v[192:195], v[66:69]
	v_mfma_f32_16x16x32_bf16 v[70:73], v[150:153], v[192:195], v[70:73]
	s_setprio 0
	s_barrier
	v_lshl_add_u64 v[196:197], s[2:3], 0, v[0:1]
	s_add_i32 s2, s67, s94
	s_mov_b32 m0, s2
	ds_read_b128 v[162:165], v225 offset:16384
	ds_read_b128 v[166:169], v225 offset:17408
	ds_read_b128 v[170:173], v225 offset:18432
	ds_read_b128 v[174:177], v225 offset:19456
	ds_read_b128 v[178:181], v225 offset:20480
	ds_read_b128 v[182:185], v225 offset:21504
	ds_read_b128 v[186:189], v225 offset:22528
	ds_read_b128 v[192:195], v225 offset:23552
	global_load_lds_dwordx4 v[196:197], off
	v_lshl_add_u64 v[198:199], v[196:197], 0, s[26:27]
	s_add_i32 m0, s2, 0x2000
	s_add_i32 s2, vcc_lo, s94
	global_load_lds_dwordx4 v[198:199], off
	v_lshl_add_u64 v[198:199], v[196:197], 0, s[20:21]
	s_mov_b32 m0, s2
	s_nop 0
	global_load_lds_dwordx4 v[198:199], off
	v_lshl_add_u64 v[198:199], v[196:197], 0, s[6:7]
	s_add_i32 m0, s2, 0x2000
	s_nop 0
	global_load_lds_dwordx4 v[198:199], off
	v_lshl_add_u64 v[198:199], s[60:61], 0, v[0:1]
	s_mov_b32 m0, s95
	v_lshl_add_u64 v[200:201], v[198:199], 0, s[26:27]
	global_load_lds_dwordx4 v[198:199], off
	s_mov_b32 m0, s42
	s_nop 0
	global_load_lds_dwordx4 v[200:201], off
	s_waitcnt vmcnt(8)
	s_waitcnt lgkmcnt(0)
	s_barrier
	s_setprio 1
	v_mfma_f32_16x16x32_bf16 v[62:65], v[126:129], v[162:165], v[62:65]
	v_mfma_f32_16x16x32_bf16 v[58:61], v[138:141], v[162:165], v[58:61]
	v_mfma_f32_16x16x32_bf16 v[42:45], v[138:141], v[170:173], v[42:45]
	v_mfma_f32_16x16x32_bf16 v[46:49], v[126:129], v[170:173], v[46:49]
	v_mfma_f32_16x16x32_bf16 v[30:33], v[126:129], v[178:181], v[30:33]
	v_mfma_f32_16x16x32_bf16 v[26:29], v[138:141], v[178:181], v[26:29]
	v_mfma_f32_16x16x32_bf16 v[10:13], v[138:141], v[186:189], v[10:13]
	v_mfma_f32_16x16x32_bf16 v[14:17], v[126:129], v[186:189], v[14:17]
	v_mfma_f32_16x16x32_bf16 v[62:65], v[134:137], v[166:169], v[62:65]
	v_mfma_f32_16x16x32_bf16 v[58:61], v[142:145], v[166:169], v[58:61]
	v_mfma_f32_16x16x32_bf16 v[42:45], v[142:145], v[174:177], v[42:45]
	v_mfma_f32_16x16x32_bf16 v[46:49], v[134:137], v[174:177], v[46:49]
	v_mfma_f32_16x16x32_bf16 v[30:33], v[134:137], v[182:185], v[30:33]
	v_mfma_f32_16x16x32_bf16 v[26:29], v[142:145], v[182:185], v[26:29]
	v_mfma_f32_16x16x32_bf16 v[10:13], v[142:145], v[192:195], v[10:13]
	v_mfma_f32_16x16x32_bf16 v[14:17], v[134:137], v[192:195], v[14:17]
	v_mfma_f32_16x16x32_bf16 v[54:57], v[146:149], v[162:165], v[54:57]
	v_mfma_f32_16x16x32_bf16 v[50:53], v[154:157], v[162:165], v[50:53]
	v_mfma_f32_16x16x32_bf16 v[34:37], v[154:157], v[170:173], v[34:37]
	v_mfma_f32_16x16x32_bf16 v[38:41], v[146:149], v[170:173], v[38:41]
	v_mfma_f32_16x16x32_bf16 v[22:25], v[146:149], v[178:181], v[22:25]
	v_mfma_f32_16x16x32_bf16 v[18:21], v[154:157], v[178:181], v[18:21]
	v_mfma_f32_16x16x32_bf16 v[2:5], v[154:157], v[186:189], v[2:5]
	v_mfma_f32_16x16x32_bf16 v[6:9], v[146:149], v[186:189], v[6:9]
	v_mfma_f32_16x16x32_bf16 v[54:57], v[150:153], v[166:169], v[54:57]
	v_mfma_f32_16x16x32_bf16 v[50:53], v[158:161], v[166:169], v[50:53]
	v_mfma_f32_16x16x32_bf16 v[34:37], v[158:161], v[174:177], v[34:37]
	v_mfma_f32_16x16x32_bf16 v[38:41], v[150:153], v[174:177], v[38:41]
	v_mfma_f32_16x16x32_bf16 v[22:25], v[150:153], v[182:185], v[22:25]
	v_mfma_f32_16x16x32_bf16 v[18:21], v[158:161], v[182:185], v[18:21]
	v_mfma_f32_16x16x32_bf16 v[2:5], v[158:161], v[192:195], v[2:5]
	v_mfma_f32_16x16x32_bf16 v[6:9], v[150:153], v[192:195], v[6:9]
	s_setprio 0
	s_barrier
	s_add_i32 s2, 0, 0x18000
	s_add_i32 s3, 0, 0x1c000
	v_add_u32_e32 v142, s2, v224
	v_add_u32_e32 v158, s3, v224
	ds_read_b128 v[126:129], v142
	ds_read_b128 v[134:137], v142 offset:1024
	ds_read_b128 v[138:141], v142 offset:2048
	ds_read_b128 v[142:145], v142 offset:3072
	ds_read_b128 v[146:149], v158
	ds_read_b128 v[150:153], v158 offset:1024
	ds_read_b128 v[154:157], v158 offset:2048
	ds_read_b128 v[158:161], v158 offset:3072
	s_mov_b32 m0, s43
	v_lshl_add_u64 v[200:201], v[198:199], 0, s[20:21]
	ds_read_b128 v[162:165], v225 offset:32768
	ds_read_b128 v[166:169], v225 offset:33792
	ds_read_b128 v[170:173], v225 offset:34816
	ds_read_b128 v[174:177], v225 offset:35840
	ds_read_b128 v[178:181], v225 offset:36864
	ds_read_b128 v[182:185], v225 offset:37888
	ds_read_b128 v[186:189], v225 offset:38912
	ds_read_b128 v[192:195], v225 offset:39936
	global_load_lds_dwordx4 v[200:201], off
	v_lshl_add_u64 v[200:201], v[198:199], 0, s[6:7]
	s_mov_b32 m0, s0
	s_nop 0
	global_load_lds_dwordx4 v[200:201], off
	s_waitcnt vmcnt(8)
	s_waitcnt lgkmcnt(0)
	s_barrier
	s_setprio 1
	v_mfma_f32_16x16x32_bf16 v[130:133], v[126:129], v[162:165], v[130:133]
	v_mfma_f32_16x16x32_bf16 v[122:125], v[138:141], v[162:165], v[122:125]
	v_mfma_f32_16x16x32_bf16 v[106:109], v[138:141], v[170:173], v[106:109]
	v_mfma_f32_16x16x32_bf16 v[110:113], v[126:129], v[170:173], v[110:113]
	v_mfma_f32_16x16x32_bf16 v[94:97], v[126:129], v[178:181], v[94:97]
	v_mfma_f32_16x16x32_bf16 v[90:93], v[138:141], v[178:181], v[90:93]
	v_mfma_f32_16x16x32_bf16 v[74:77], v[138:141], v[186:189], v[74:77]
	v_mfma_f32_16x16x32_bf16 v[78:81], v[126:129], v[186:189], v[78:81]
	v_mfma_f32_16x16x32_bf16 v[130:133], v[134:137], v[166:169], v[130:133]
	v_mfma_f32_16x16x32_bf16 v[122:125], v[142:145], v[166:169], v[122:125]
	v_mfma_f32_16x16x32_bf16 v[106:109], v[142:145], v[174:177], v[106:109]
	v_mfma_f32_16x16x32_bf16 v[110:113], v[134:137], v[174:177], v[110:113]
	v_mfma_f32_16x16x32_bf16 v[94:97], v[134:137], v[182:185], v[94:97]
	v_mfma_f32_16x16x32_bf16 v[90:93], v[142:145], v[182:185], v[90:93]
	v_mfma_f32_16x16x32_bf16 v[74:77], v[142:145], v[192:195], v[74:77]
	v_mfma_f32_16x16x32_bf16 v[78:81], v[134:137], v[192:195], v[78:81]
	v_mfma_f32_16x16x32_bf16 v[118:121], v[146:149], v[162:165], v[118:121]
	v_mfma_f32_16x16x32_bf16 v[114:117], v[154:157], v[162:165], v[114:117]
	v_mfma_f32_16x16x32_bf16 v[98:101], v[154:157], v[170:173], v[98:101]
	v_mfma_f32_16x16x32_bf16 v[102:105], v[146:149], v[170:173], v[102:105]
	v_mfma_f32_16x16x32_bf16 v[86:89], v[146:149], v[178:181], v[86:89]
	v_mfma_f32_16x16x32_bf16 v[82:85], v[154:157], v[178:181], v[82:85]
	v_mfma_f32_16x16x32_bf16 v[66:69], v[154:157], v[186:189], v[66:69]
	v_mfma_f32_16x16x32_bf16 v[70:73], v[146:149], v[186:189], v[70:73]
	v_mfma_f32_16x16x32_bf16 v[118:121], v[150:153], v[166:169], v[118:121]
	v_mfma_f32_16x16x32_bf16 v[114:117], v[158:161], v[166:169], v[114:117]
	v_mfma_f32_16x16x32_bf16 v[98:101], v[158:161], v[174:177], v[98:101]
	v_mfma_f32_16x16x32_bf16 v[102:105], v[150:153], v[174:177], v[102:105]
	v_mfma_f32_16x16x32_bf16 v[86:89], v[150:153], v[182:185], v[86:89]
	v_mfma_f32_16x16x32_bf16 v[82:85], v[158:161], v[182:185], v[82:85]
	v_mfma_f32_16x16x32_bf16 v[66:69], v[158:161], v[192:195], v[66:69]
	v_mfma_f32_16x16x32_bf16 v[70:73], v[150:153], v[192:195], v[70:73]
	s_setprio 0
	s_barrier
	s_add_i32 s2, s2, s94
	v_lshl_add_u64 v[200:201], v[196:197], 0, s[30:31]
	s_mov_b32 m0, s2
	ds_read_b128 v[162:165], v225 offset:49152
	ds_read_b128 v[166:169], v225 offset:50176
	ds_read_b128 v[170:173], v225 offset:51200
	ds_read_b128 v[174:177], v225 offset:52224
	ds_read_b128 v[178:181], v225 offset:53248
	ds_read_b128 v[182:185], v225 offset:54272
	ds_read_b128 v[186:189], v225 offset:55296
	ds_read_b128 v[192:195], v225 offset:56320
	global_load_lds_dwordx4 v[200:201], off
	v_lshl_add_u64 v[200:201], v[196:197], 0, s[50:51]
	s_add_i32 m0, s2, 0x2000
	s_add_i32 s2, s3, s94
	global_load_lds_dwordx4 v[200:201], off
	v_lshl_add_u64 v[200:201], v[196:197], 0, s[36:37]
	s_mov_b32 m0, s2
	v_lshl_add_u64 v[196:197], v[196:197], 0, s[88:89]
	global_load_lds_dwordx4 v[200:201], off
	s_add_i32 m0, s2, 0x2000
	s_nop 0
	global_load_lds_dwordx4 v[196:197], off
	v_lshl_add_u64 v[196:197], v[198:199], 0, s[30:31]
	s_mov_b32 m0, s41
	s_nop 0
	global_load_lds_dwordx4 v[196:197], off
	v_lshl_add_u64 v[196:197], v[198:199], 0, s[50:51]
	s_mov_b32 m0, s96
	s_nop 0
	global_load_lds_dwordx4 v[196:197], off
	s_waitcnt vmcnt(8)
	s_waitcnt lgkmcnt(0)
	s_barrier
	s_setprio 1
	v_mfma_f32_16x16x32_bf16 v[62:65], v[126:129], v[162:165], v[62:65]
	v_mfma_f32_16x16x32_bf16 v[58:61], v[138:141], v[162:165], v[58:61]
	v_mfma_f32_16x16x32_bf16 v[42:45], v[138:141], v[170:173], v[42:45]
	v_mfma_f32_16x16x32_bf16 v[46:49], v[126:129], v[170:173], v[46:49]
	v_mfma_f32_16x16x32_bf16 v[30:33], v[126:129], v[178:181], v[30:33]
	v_mfma_f32_16x16x32_bf16 v[26:29], v[138:141], v[178:181], v[26:29]
	v_mfma_f32_16x16x32_bf16 v[10:13], v[138:141], v[186:189], v[10:13]
	v_mfma_f32_16x16x32_bf16 v[14:17], v[126:129], v[186:189], v[14:17]
	v_mfma_f32_16x16x32_bf16 v[62:65], v[134:137], v[166:169], v[62:65]
	v_mfma_f32_16x16x32_bf16 v[58:61], v[142:145], v[166:169], v[58:61]
	v_mfma_f32_16x16x32_bf16 v[42:45], v[142:145], v[174:177], v[42:45]
	v_mfma_f32_16x16x32_bf16 v[46:49], v[134:137], v[174:177], v[46:49]
	v_mfma_f32_16x16x32_bf16 v[30:33], v[134:137], v[182:185], v[30:33]
	v_mfma_f32_16x16x32_bf16 v[26:29], v[142:145], v[182:185], v[26:29]
	v_mfma_f32_16x16x32_bf16 v[10:13], v[142:145], v[192:195], v[10:13]
	v_mfma_f32_16x16x32_bf16 v[14:17], v[134:137], v[192:195], v[14:17]
	v_mfma_f32_16x16x32_bf16 v[54:57], v[146:149], v[162:165], v[54:57]
	v_mfma_f32_16x16x32_bf16 v[50:53], v[154:157], v[162:165], v[50:53]
	v_mfma_f32_16x16x32_bf16 v[34:37], v[154:157], v[170:173], v[34:37]
	v_mfma_f32_16x16x32_bf16 v[38:41], v[146:149], v[170:173], v[38:41]
	v_mfma_f32_16x16x32_bf16 v[22:25], v[146:149], v[178:181], v[22:25]
	v_mfma_f32_16x16x32_bf16 v[18:21], v[154:157], v[178:181], v[18:21]
	v_mfma_f32_16x16x32_bf16 v[2:5], v[154:157], v[186:189], v[2:5]
	v_mfma_f32_16x16x32_bf16 v[6:9], v[146:149], v[186:189], v[6:9]
	v_mfma_f32_16x16x32_bf16 v[54:57], v[150:153], v[166:169], v[54:57]
	v_mfma_f32_16x16x32_bf16 v[50:53], v[158:161], v[166:169], v[50:53]
	v_mfma_f32_16x16x32_bf16 v[34:37], v[158:161], v[174:177], v[34:37]
	v_mfma_f32_16x16x32_bf16 v[38:41], v[150:153], v[174:177], v[38:41]
	v_mfma_f32_16x16x32_bf16 v[22:25], v[150:153], v[182:185], v[22:25]
	v_mfma_f32_16x16x32_bf16 v[18:21], v[158:161], v[182:185], v[18:21]
	v_mfma_f32_16x16x32_bf16 v[2:5], v[158:161], v[192:195], v[2:5]
	v_mfma_f32_16x16x32_bf16 v[6:9], v[150:153], v[192:195], v[6:9]
	s_setprio 0
	s_barrier
	s_add_i32 s66, s66, 2
	s_add_u32 s58, s58, 0x100
	s_addc_u32 s59, s59, 0
	s_add_u32 s64, s64, 0x100
	s_addc_u32 s65, s65, 0
	s_cmp_gt_u32 s66, 29
	s_cbranch_scc0 .LBB0_406
	s_and_b64 vcc, exec, s[44:45]
	s_cbranch_vccz .LBB0_409
	s_barrier

.LBB0_447:
	s_add_u32 s2, s52, 0xfff80080
	s_addc_u32 s3, s53, -1
	s_add_i32 s96, 0, 0x10000
	s_cmp_eq_u32 s95, 28
	s_cselect_b32 s55, s45, s3
	s_cselect_b32 s54, s67, s2
	s_cselect_b32 s3, s43, s94
	s_cselect_b32 s2, s90, s91
	s_add_i32 s97, 0, 0x14000
	v_add_u32_e32 v146, s96, v152
	v_add_u32_e32 v150, s97, v152
	ds_read_b128 v[134:137], v146
	ds_read_b128 v[138:141], v146 offset:1024
	ds_read_b128 v[142:145], v146 offset:2048
	ds_read_b128 v[146:149], v146 offset:3072
	ds_read_b128 v[154:157], v150
	ds_read_b128 v[158:161], v150 offset:1024
	ds_read_b128 v[162:165], v150 offset:2048
	ds_read_b128 v[166:169], v150 offset:3072
	v_lshl_add_u64 v[150:151], s[52:53], 0, v[132:133]
	s_add_i32 m0, s58, 0xc000
	ds_read_b128 v[170:173], v153
	ds_read_b128 v[174:177], v153 offset:1024
	ds_read_b128 v[178:181], v153 offset:2048
	ds_read_b128 v[182:185], v153 offset:3072
	ds_read_b128 v[186:189], v153 offset:4096
	ds_read_b128 v[190:193], v153 offset:5120
	ds_read_b128 v[206:209], v153 offset:6144
	ds_read_b128 v[210:213], v153 offset:7168
	global_load_lds_dwordx4 v[150:151], off
	v_lshl_add_u64 v[150:151], v[150:151], 0, s[26:27]
	s_add_i32 m0, s58, 0xe000
	s_nop 0
	global_load_lds_dwordx4 v[150:151], off
	s_waitcnt vmcnt(8)
	s_waitcnt lgkmcnt(0)
	s_barrier
	s_setprio 1
	v_mfma_f32_16x16x32_bf16 v[126:129], v[134:137], v[170:173], v[126:129]
	v_mfma_f32_16x16x32_bf16 v[122:125], v[142:145], v[170:173], v[122:125]
	v_mfma_f32_16x16x32_bf16 v[106:109], v[142:145], v[178:181], v[106:109]
	v_mfma_f32_16x16x32_bf16 v[110:113], v[134:137], v[178:181], v[110:113]
	v_mfma_f32_16x16x32_bf16 v[94:97], v[134:137], v[186:189], v[94:97]
	v_mfma_f32_16x16x32_bf16 v[90:93], v[142:145], v[186:189], v[90:93]
	v_mfma_f32_16x16x32_bf16 v[74:77], v[142:145], v[206:209], v[74:77]
	v_mfma_f32_16x16x32_bf16 v[78:81], v[134:137], v[206:209], v[78:81]
	v_mfma_f32_16x16x32_bf16 v[126:129], v[138:141], v[174:177], v[126:129]
	v_mfma_f32_16x16x32_bf16 v[122:125], v[146:149], v[174:177], v[122:125]
	v_mfma_f32_16x16x32_bf16 v[106:109], v[146:149], v[182:185], v[106:109]
	v_mfma_f32_16x16x32_bf16 v[110:113], v[138:141], v[182:185], v[110:113]
	v_mfma_f32_16x16x32_bf16 v[94:97], v[138:141], v[190:193], v[94:97]
	v_mfma_f32_16x16x32_bf16 v[90:93], v[146:149], v[190:193], v[90:93]
	v_mfma_f32_16x16x32_bf16 v[74:77], v[146:149], v[210:213], v[74:77]
	v_mfma_f32_16x16x32_bf16 v[78:81], v[138:141], v[210:213], v[78:81]
	v_mfma_f32_16x16x32_bf16 v[118:121], v[154:157], v[170:173], v[118:121]
	v_mfma_f32_16x16x32_bf16 v[114:117], v[162:165], v[170:173], v[114:117]
	v_mfma_f32_16x16x32_bf16 v[98:101], v[162:165], v[178:181], v[98:101]
	v_mfma_f32_16x16x32_bf16 v[102:105], v[154:157], v[178:181], v[102:105]
	v_mfma_f32_16x16x32_bf16 v[86:89], v[154:157], v[186:189], v[86:89]
	v_mfma_f32_16x16x32_bf16 v[82:85], v[162:165], v[186:189], v[82:85]
	v_mfma_f32_16x16x32_bf16 v[66:69], v[162:165], v[206:209], v[66:69]
	v_mfma_f32_16x16x32_bf16 v[70:73], v[154:157], v[206:209], v[70:73]
	v_mfma_f32_16x16x32_bf16 v[118:121], v[158:161], v[174:177], v[118:121]
	v_mfma_f32_16x16x32_bf16 v[114:117], v[166:169], v[174:177], v[114:117]
	v_mfma_f32_16x16x32_bf16 v[98:101], v[166:169], v[182:185], v[98:101]
	v_mfma_f32_16x16x32_bf16 v[102:105], v[158:161], v[182:185], v[102:105]
	v_mfma_f32_16x16x32_bf16 v[86:89], v[158:161], v[190:193], v[86:89]
	v_mfma_f32_16x16x32_bf16 v[82:85], v[166:169], v[190:193], v[82:85]
	v_mfma_f32_16x16x32_bf16 v[66:69], v[166:169], v[210:213], v[66:69]
	v_mfma_f32_16x16x32_bf16 v[70:73], v[158:161], v[210:213], v[70:73]
	s_setprio 0
	s_barrier
	v_lshl_add_u64 v[150:151], s[2:3], 0, v[0:1]
	s_add_i32 s2, s96, s57
	s_mov_b32 m0, s2
	ds_read_b128 v[170:173], v153 offset:16384
	ds_read_b128 v[174:177], v153 offset:17408
	ds_read_b128 v[178:181], v153 offset:18432
	ds_read_b128 v[182:185], v153 offset:19456
	ds_read_b128 v[186:189], v153 offset:20480
	ds_read_b128 v[190:193], v153 offset:21504
	ds_read_b128 v[206:209], v153 offset:22528
	ds_read_b128 v[210:213], v153 offset:23552
	global_load_lds_dwordx4 v[150:151], off
	v_lshl_add_u64 v[194:195], v[150:151], 0, s[26:27]
	s_add_i32 m0, s2, 0x2000
	s_add_i32 s2, s97, s57
	global_load_lds_dwordx4 v[194:195], off
	v_lshl_add_u64 v[194:195], v[150:151], 0, s[20:21]
	s_mov_b32 m0, s2
	s_nop 0
	global_load_lds_dwordx4 v[194:195], off
	v_lshl_add_u64 v[194:195], v[150:151], 0, s[6:7]
	s_add_i32 m0, s2, 0x2000
	s_nop 0
	global_load_lds_dwordx4 v[194:195], off
	v_lshl_add_u64 v[194:195], s[54:55], 0, v[130:131]
	s_mov_b32 m0, s58
	v_lshl_add_u64 v[196:197], v[194:195], 0, s[26:27]
	global_load_lds_dwordx4 v[194:195], off
	s_mov_b32 m0, s59
	s_nop 0
	global_load_lds_dwordx4 v[196:197], off
	s_waitcnt vmcnt(8)
	s_waitcnt lgkmcnt(0)
	s_barrier
	s_setprio 1
	v_mfma_f32_16x16x32_bf16 v[62:65], v[134:137], v[170:173], v[62:65]
	v_mfma_f32_16x16x32_bf16 v[58:61], v[142:145], v[170:173], v[58:61]
	v_mfma_f32_16x16x32_bf16 v[42:45], v[142:145], v[178:181], v[42:45]
	v_mfma_f32_16x16x32_bf16 v[46:49], v[134:137], v[178:181], v[46:49]
	v_mfma_f32_16x16x32_bf16 v[30:33], v[134:137], v[186:189], v[30:33]
	v_mfma_f32_16x16x32_bf16 v[26:29], v[142:145], v[186:189], v[26:29]
	v_mfma_f32_16x16x32_bf16 v[10:13], v[142:145], v[206:209], v[10:13]
	v_mfma_f32_16x16x32_bf16 v[14:17], v[134:137], v[206:209], v[14:17]
	v_mfma_f32_16x16x32_bf16 v[62:65], v[138:141], v[174:177], v[62:65]
	v_mfma_f32_16x16x32_bf16 v[58:61], v[146:149], v[174:177], v[58:61]
	v_mfma_f32_16x16x32_bf16 v[42:45], v[146:149], v[182:185], v[42:45]
	v_mfma_f32_16x16x32_bf16 v[46:49], v[138:141], v[182:185], v[46:49]
	v_mfma_f32_16x16x32_bf16 v[30:33], v[138:141], v[190:193], v[30:33]
	v_mfma_f32_16x16x32_bf16 v[26:29], v[146:149], v[190:193], v[26:29]
	v_mfma_f32_16x16x32_bf16 v[10:13], v[146:149], v[210:213], v[10:13]
	v_mfma_f32_16x16x32_bf16 v[14:17], v[138:141], v[210:213], v[14:17]
	v_mfma_f32_16x16x32_bf16 v[54:57], v[154:157], v[170:173], v[54:57]
	v_mfma_f32_16x16x32_bf16 v[50:53], v[162:165], v[170:173], v[50:53]
	v_mfma_f32_16x16x32_bf16 v[34:37], v[162:165], v[178:181], v[34:37]
	v_mfma_f32_16x16x32_bf16 v[38:41], v[154:157], v[178:181], v[38:41]
	v_mfma_f32_16x16x32_bf16 v[22:25], v[154:157], v[186:189], v[22:25]
	v_mfma_f32_16x16x32_bf16 v[18:21], v[162:165], v[186:189], v[18:21]
	v_mfma_f32_16x16x32_bf16 v[2:5], v[162:165], v[206:209], v[2:5]
	v_mfma_f32_16x16x32_bf16 v[6:9], v[154:157], v[206:209], v[6:9]
	v_mfma_f32_16x16x32_bf16 v[54:57], v[158:161], v[174:177], v[54:57]
	v_mfma_f32_16x16x32_bf16 v[50:53], v[166:169], v[174:177], v[50:53]
	v_mfma_f32_16x16x32_bf16 v[34:37], v[166:169], v[182:185], v[34:37]
	v_mfma_f32_16x16x32_bf16 v[38:41], v[158:161], v[182:185], v[38:41]
	v_mfma_f32_16x16x32_bf16 v[22:25], v[158:161], v[190:193], v[22:25]
	v_mfma_f32_16x16x32_bf16 v[18:21], v[166:169], v[190:193], v[18:21]
	v_mfma_f32_16x16x32_bf16 v[2:5], v[166:169], v[210:213], v[2:5]
	v_mfma_f32_16x16x32_bf16 v[6:9], v[158:161], v[210:213], v[6:9]
	s_setprio 0
	s_barrier
	s_add_i32 s2, 0, 0x18000
	s_add_i32 s3, 0, 0x1c000
	v_add_u32_e32 v146, s2, v152
	v_add_u32_e32 v166, s3, v152
	ds_read_b128 v[134:137], v146
	ds_read_b128 v[138:141], v146 offset:1024
	ds_read_b128 v[142:145], v146 offset:2048
	ds_read_b128 v[146:149], v146 offset:3072
	ds_read_b128 v[154:157], v166
	ds_read_b128 v[158:161], v166 offset:1024
	ds_read_b128 v[162:165], v166 offset:2048
	ds_read_b128 v[166:169], v166 offset:3072
	s_mov_b32 m0, s60
	v_lshl_add_u64 v[196:197], v[194:195], 0, s[20:21]
	ds_read_b128 v[170:173], v153 offset:32768
	ds_read_b128 v[174:177], v153 offset:33792
	ds_read_b128 v[178:181], v153 offset:34816
	ds_read_b128 v[182:185], v153 offset:35840
	ds_read_b128 v[186:189], v153 offset:36864
	ds_read_b128 v[190:193], v153 offset:37888
	ds_read_b128 v[206:209], v153 offset:38912
	ds_read_b128 v[210:213], v153 offset:39936
	global_load_lds_dwordx4 v[196:197], off
	v_lshl_add_u64 v[196:197], v[194:195], 0, s[6:7]
	s_mov_b32 m0, s61
	s_nop 0
	global_load_lds_dwordx4 v[196:197], off
	s_waitcnt vmcnt(8)
	s_waitcnt lgkmcnt(0)
	s_barrier
	s_setprio 1
	v_mfma_f32_16x16x32_bf16 v[126:129], v[134:137], v[170:173], v[126:129]
	v_mfma_f32_16x16x32_bf16 v[122:125], v[142:145], v[170:173], v[122:125]
	v_mfma_f32_16x16x32_bf16 v[106:109], v[142:145], v[178:181], v[106:109]
	v_mfma_f32_16x16x32_bf16 v[110:113], v[134:137], v[178:181], v[110:113]
	v_mfma_f32_16x16x32_bf16 v[94:97], v[134:137], v[186:189], v[94:97]
	v_mfma_f32_16x16x32_bf16 v[90:93], v[142:145], v[186:189], v[90:93]
	v_mfma_f32_16x16x32_bf16 v[74:77], v[142:145], v[206:209], v[74:77]
	v_mfma_f32_16x16x32_bf16 v[78:81], v[134:137], v[206:209], v[78:81]
	v_mfma_f32_16x16x32_bf16 v[126:129], v[138:141], v[174:177], v[126:129]
	v_mfma_f32_16x16x32_bf16 v[122:125], v[146:149], v[174:177], v[122:125]
	v_mfma_f32_16x16x32_bf16 v[106:109], v[146:149], v[182:185], v[106:109]
	v_mfma_f32_16x16x32_bf16 v[110:113], v[138:141], v[182:185], v[110:113]
	v_mfma_f32_16x16x32_bf16 v[94:97], v[138:141], v[190:193], v[94:97]
	v_mfma_f32_16x16x32_bf16 v[90:93], v[146:149], v[190:193], v[90:93]
	v_mfma_f32_16x16x32_bf16 v[74:77], v[146:149], v[210:213], v[74:77]
	v_mfma_f32_16x16x32_bf16 v[78:81], v[138:141], v[210:213], v[78:81]
	v_mfma_f32_16x16x32_bf16 v[118:121], v[154:157], v[170:173], v[118:121]
	v_mfma_f32_16x16x32_bf16 v[114:117], v[162:165], v[170:173], v[114:117]
	v_mfma_f32_16x16x32_bf16 v[98:101], v[162:165], v[178:181], v[98:101]
	v_mfma_f32_16x16x32_bf16 v[102:105], v[154:157], v[178:181], v[102:105]
	v_mfma_f32_16x16x32_bf16 v[86:89], v[154:157], v[186:189], v[86:89]
	v_mfma_f32_16x16x32_bf16 v[82:85], v[162:165], v[186:189], v[82:85]
	v_mfma_f32_16x16x32_bf16 v[66:69], v[162:165], v[206:209], v[66:69]
	v_mfma_f32_16x16x32_bf16 v[70:73], v[154:157], v[206:209], v[70:73]
	v_mfma_f32_16x16x32_bf16 v[118:121], v[158:161], v[174:177], v[118:121]
	v_mfma_f32_16x16x32_bf16 v[114:117], v[166:169], v[174:177], v[114:117]
	v_mfma_f32_16x16x32_bf16 v[98:101], v[166:169], v[182:185], v[98:101]
	v_mfma_f32_16x16x32_bf16 v[102:105], v[158:161], v[182:185], v[102:105]
	v_mfma_f32_16x16x32_bf16 v[86:89], v[158:161], v[190:193], v[86:89]
	v_mfma_f32_16x16x32_bf16 v[82:85], v[166:169], v[190:193], v[82:85]
	v_mfma_f32_16x16x32_bf16 v[66:69], v[166:169], v[210:213], v[66:69]
	v_mfma_f32_16x16x32_bf16 v[70:73], v[158:161], v[210:213], v[70:73]
	s_setprio 0
	s_barrier
	s_add_i32 s2, s2, s57
	v_lshl_add_u64 v[196:197], v[150:151], 0, s[30:31]
	s_mov_b32 m0, s2
	ds_read_b128 v[170:173], v153 offset:49152
	ds_read_b128 v[174:177], v153 offset:50176
	ds_read_b128 v[178:181], v153 offset:51200
	ds_read_b128 v[182:185], v153 offset:52224
	ds_read_b128 v[186:189], v153 offset:53248
	ds_read_b128 v[190:193], v153 offset:54272
	ds_read_b128 v[206:209], v153 offset:55296
	ds_read_b128 v[210:213], v153 offset:56320
	global_load_lds_dwordx4 v[196:197], off
	v_lshl_add_u64 v[196:197], v[150:151], 0, s[50:51]
	s_add_i32 m0, s2, 0x2000
	s_add_i32 s2, s3, s57
	global_load_lds_dwordx4 v[196:197], off
	v_lshl_add_u64 v[196:197], v[150:151], 0, s[36:37]
	s_mov_b32 m0, s2
	v_lshl_add_u64 v[150:151], v[150:151], 0, s[88:89]
	global_load_lds_dwordx4 v[196:197], off
	s_add_i32 m0, s2, 0x2000
	s_nop 0
	global_load_lds_dwordx4 v[150:151], off
	v_lshl_add_u64 v[150:151], v[194:195], 0, s[30:31]
	s_mov_b32 m0, s62
	s_nop 0
	global_load_lds_dwordx4 v[150:151], off
	v_lshl_add_u64 v[150:151], v[194:195], 0, s[50:51]
	s_mov_b32 m0, s63
	s_nop 0
	global_load_lds_dwordx4 v[150:151], off
	s_waitcnt vmcnt(8)
	s_waitcnt lgkmcnt(0)
	s_barrier
	s_setprio 1
	v_mfma_f32_16x16x32_bf16 v[62:65], v[134:137], v[170:173], v[62:65]
	v_mfma_f32_16x16x32_bf16 v[58:61], v[142:145], v[170:173], v[58:61]
	v_mfma_f32_16x16x32_bf16 v[42:45], v[142:145], v[178:181], v[42:45]
	v_mfma_f32_16x16x32_bf16 v[46:49], v[134:137], v[178:181], v[46:49]
	v_mfma_f32_16x16x32_bf16 v[30:33], v[134:137], v[186:189], v[30:33]
	v_mfma_f32_16x16x32_bf16 v[26:29], v[142:145], v[186:189], v[26:29]
	v_mfma_f32_16x16x32_bf16 v[10:13], v[142:145], v[206:209], v[10:13]
	v_mfma_f32_16x16x32_bf16 v[14:17], v[134:137], v[206:209], v[14:17]
	v_mfma_f32_16x16x32_bf16 v[62:65], v[138:141], v[174:177], v[62:65]
	v_mfma_f32_16x16x32_bf16 v[58:61], v[146:149], v[174:177], v[58:61]
	v_mfma_f32_16x16x32_bf16 v[42:45], v[146:149], v[182:185], v[42:45]
	v_mfma_f32_16x16x32_bf16 v[46:49], v[138:141], v[182:185], v[46:49]
	v_mfma_f32_16x16x32_bf16 v[30:33], v[138:141], v[190:193], v[30:33]
	v_mfma_f32_16x16x32_bf16 v[26:29], v[146:149], v[190:193], v[26:29]
	v_mfma_f32_16x16x32_bf16 v[10:13], v[146:149], v[210:213], v[10:13]
	v_mfma_f32_16x16x32_bf16 v[14:17], v[138:141], v[210:213], v[14:17]
	v_mfma_f32_16x16x32_bf16 v[54:57], v[154:157], v[170:173], v[54:57]
	v_mfma_f32_16x16x32_bf16 v[50:53], v[162:165], v[170:173], v[50:53]
	v_mfma_f32_16x16x32_bf16 v[34:37], v[162:165], v[178:181], v[34:37]
	v_mfma_f32_16x16x32_bf16 v[38:41], v[154:157], v[178:181], v[38:41]
	v_mfma_f32_16x16x32_bf16 v[22:25], v[154:157], v[186:189], v[22:25]
	v_mfma_f32_16x16x32_bf16 v[18:21], v[162:165], v[186:189], v[18:21]
	v_mfma_f32_16x16x32_bf16 v[2:5], v[162:165], v[206:209], v[2:5]
	v_mfma_f32_16x16x32_bf16 v[6:9], v[154:157], v[206:209], v[6:9]
	v_mfma_f32_16x16x32_bf16 v[54:57], v[158:161], v[174:177], v[54:57]
	v_mfma_f32_16x16x32_bf16 v[50:53], v[166:169], v[174:177], v[50:53]
	v_mfma_f32_16x16x32_bf16 v[34:37], v[166:169], v[182:185], v[34:37]
	v_mfma_f32_16x16x32_bf16 v[38:41], v[158:161], v[182:185], v[38:41]
	v_mfma_f32_16x16x32_bf16 v[22:25], v[158:161], v[190:193], v[22:25]
	v_mfma_f32_16x16x32_bf16 v[18:21], v[166:169], v[190:193], v[18:21]
	v_mfma_f32_16x16x32_bf16 v[2:5], v[166:169], v[210:213], v[2:5]
	v_mfma_f32_16x16x32_bf16 v[6:9], v[158:161], v[210:213], v[6:9]
	s_setprio 0
	s_barrier
	s_add_i32 s95, s95, 2
	s_add_u32 s52, s52, 0x100
	s_addc_u32 s53, s53, 0
	s_add_u32 s91, s91, 0x100
	s_addc_u32 s94, s94, 0
	s_cmp_gt_u32 s95, 29
	s_cbranch_scc0 .LBB0_447
	s_and_b64 vcc, exec, s[40:41]
	s_cbranch_vccz .LBB0_450
	s_barrier

.LBB0_561:
	s_add_u32 s2, s52, 0xfffc0080
	s_addc_u32 s3, s53, -1
	s_add_i32 vcc_lo, 0, 0x10000
	s_cmp_eq_u32 s97, 12
	s_cselect_b32 s55, s12, s3
	s_cselect_b32 s54, s45, s2
	v_add_u32_e32 v132, vcc_lo, v136
	s_cselect_b32 s57, s43, s96
	s_cselect_b32 s56, s94, s95
	s_add_i32 s2, 0, 0x14000
	ds_read_b128 v[138:141], v132
	ds_read_b128 v[142:145], v132 offset:1024
	ds_read_b128 v[146:149], v132 offset:2048
	ds_read_b128 v[150:153], v132 offset:3072
	v_add_u32_e32 v132, s2, v136
	ds_read_b128 v[154:157], v132
	ds_read_b128 v[158:161], v132 offset:1024
	ds_read_b128 v[162:165], v132 offset:2048
	ds_read_b128 v[166:169], v132 offset:3072
	v_lshl_add_u64 v[132:133], s[52:53], 0, v[130:131]
	s_add_i32 m0, s60, 0xc000
	ds_read_b128 v[170:173], v137
	ds_read_b128 v[174:177], v137 offset:1024
	ds_read_b128 v[178:181], v137 offset:2048
	ds_read_b128 v[182:185], v137 offset:3072
	ds_read_b128 v[186:189], v137 offset:4096
	ds_read_b128 v[190:193], v137 offset:5120
	ds_read_b128 v[206:209], v137 offset:6144
	ds_read_b128 v[210:213], v137 offset:7168
	global_load_lds_dwordx4 v[132:133], off
	v_lshl_add_u64 v[132:133], v[132:133], 0, s[10:11]
	s_add_i32 m0, s60, 0xe000
	s_nop 0
	global_load_lds_dwordx4 v[132:133], off
	s_waitcnt vmcnt(8)
	s_waitcnt lgkmcnt(0)
	s_barrier
	s_setprio 1
	v_mfma_f32_16x16x128_f8f6f4 v[126:129], v[138:145], v[170:177], v[126:129]
	v_mfma_f32_16x16x128_f8f6f4 v[122:125], v[146:153], v[170:177], v[122:125]
	v_mfma_f32_16x16x128_f8f6f4 v[106:109], v[146:153], v[178:185], v[106:109]
	v_mfma_f32_16x16x128_f8f6f4 v[110:113], v[138:145], v[178:185], v[110:113]
	v_mfma_f32_16x16x128_f8f6f4 v[132:135], v[138:145], v[186:193], v[94:97]
	v_mfma_f32_16x16x128_f8f6f4 v[214:217], v[146:153], v[186:193], v[90:93]
	v_mfma_f32_16x16x128_f8f6f4 v[222:225], v[146:153], v[206:213], v[74:77]
	v_mfma_f32_16x16x128_f8f6f4 v[218:221], v[138:145], v[206:213], v[78:81]
	v_mfma_f32_16x16x128_f8f6f4 v[118:121], v[154:161], v[170:177], v[118:121]
	v_mfma_f32_16x16x128_f8f6f4 v[114:117], v[162:169], v[170:177], v[114:117]
	v_mfma_f32_16x16x128_f8f6f4 v[98:101], v[162:169], v[178:185], v[98:101]
	v_mfma_f32_16x16x128_f8f6f4 v[102:105], v[154:161], v[178:185], v[102:105]
	v_mfma_f32_16x16x128_f8f6f4 v[170:173], v[154:161], v[186:193], v[86:89]
	v_mfma_f32_16x16x128_f8f6f4 v[174:177], v[162:169], v[186:193], v[82:85]
	v_mfma_f32_16x16x128_f8f6f4 v[182:185], v[162:169], v[206:213], v[66:69]
	v_mfma_f32_16x16x128_f8f6f4 v[178:181], v[154:161], v[206:213], v[70:73]
	s_setprio 0
	s_barrier
	s_add_i32 s3, vcc_lo, s59
	v_lshl_add_u64 v[232:233], s[56:57], 0, v[0:1]
	s_mov_b32 m0, s3
	s_nop 1
	ds_read_b128 v[66:69], v137 offset:16384
	ds_read_b128 v[70:73], v137 offset:17408
	ds_read_b128 v[74:77], v137 offset:18432
	ds_read_b128 v[78:81], v137 offset:19456
	ds_read_b128 v[82:85], v137 offset:20480
	ds_read_b128 v[86:89], v137 offset:21504
	ds_read_b128 v[90:93], v137 offset:22528
	ds_read_b128 v[94:97], v137 offset:23552
	global_load_lds_dwordx4 v[232:233], off
	v_lshl_add_u64 v[186:187], v[232:233], 0, s[10:11]
	s_add_i32 m0, s3, 0x2000
	s_add_i32 s2, s2, s59
	global_load_lds_dwordx4 v[186:187], off
	v_lshl_add_u64 v[186:187], v[232:233], 0, s[26:27]
	s_mov_b32 m0, s2
	v_lshl_add_u64 v[230:231], s[54:55], 0, v[0:1]
	global_load_lds_dwordx4 v[186:187], off
	v_lshl_add_u64 v[186:187], v[232:233], 0, s[14:15]
	s_add_i32 m0, s2, 0x2000
	s_nop 0
	global_load_lds_dwordx4 v[186:187], off
	s_mov_b32 m0, s60
	v_lshl_add_u64 v[186:187], v[230:231], 0, s[10:11]
	global_load_lds_dwordx4 v[230:231], off
	s_mov_b32 m0, s61
	s_nop 0
	global_load_lds_dwordx4 v[186:187], off
	s_waitcnt vmcnt(8)
	s_waitcnt lgkmcnt(0)
	s_barrier
	s_setprio 1
	v_mfma_f32_16x16x128_f8f6f4 v[62:65], v[138:145], v[66:73], v[62:65]
	v_mfma_f32_16x16x128_f8f6f4 v[58:61], v[146:153], v[66:73], v[58:61]
	v_mfma_f32_16x16x128_f8f6f4 v[190:193], v[146:153], v[74:81], v[42:45]
	v_mfma_f32_16x16x128_f8f6f4 v[186:189], v[138:145], v[74:81], v[46:49]
	v_mfma_f32_16x16x128_f8f6f4 v[206:209], v[138:145], v[82:89], v[30:33]
	v_mfma_f32_16x16x128_f8f6f4 v[210:213], v[146:153], v[82:89], v[26:29]
	v_mfma_f32_16x16x128_f8f6f4 v[246:249], v[146:153], v[90:97], v[10:13]
	v_mfma_f32_16x16x128_f8f6f4 v[242:245], v[138:145], v[90:97], v[14:17]
	v_mfma_f32_16x16x128_f8f6f4 v[54:57], v[154:161], v[66:73], v[54:57]
	v_mfma_f32_16x16x128_f8f6f4 v[50:53], v[162:169], v[66:73], v[50:53]
	v_mfma_f32_16x16x128_f8f6f4 v[198:201], v[162:169], v[74:81], v[34:37]
	v_mfma_f32_16x16x128_f8f6f4 v[234:237], v[154:161], v[74:81], v[38:41]
	v_mfma_f32_16x16x128_f8f6f4 v[202:205], v[154:161], v[82:89], v[22:25]
	v_mfma_f32_16x16x128_f8f6f4 v[194:197], v[162:169], v[82:89], v[18:21]
	v_mfma_f32_16x16x128_f8f6f4 v[226:229], v[162:169], v[90:97], v[2:5]
	v_mfma_f32_16x16x128_f8f6f4 v[238:241], v[154:161], v[90:97], v[6:9]
	s_setprio 0
	s_barrier
	s_add_i32 s2, 0, 0x18000
	v_add_u32_e32 v10, s2, v136
	s_add_i32 s3, 0, 0x1c000
	s_nop 1
	ds_read_b128 v[2:5], v10
	ds_read_b128 v[6:9], v10 offset:1024
	ds_read_b128 v[18:21], v10 offset:2048
	ds_read_b128 v[22:25], v10 offset:3072
	v_add_u32_e32 v10, s3, v136
	ds_read_b128 v[138:141], v10
	ds_read_b128 v[142:145], v10 offset:1024
	ds_read_b128 v[146:149], v10 offset:2048
	ds_read_b128 v[150:153], v10 offset:3072
	s_mov_b32 m0, s62
	v_lshl_add_u64 v[66:67], v[230:231], 0, s[26:27]
	ds_read_b128 v[10:13], v137 offset:32768
	ds_read_b128 v[14:17], v137 offset:33792
	ds_read_b128 v[26:29], v137 offset:34816
	ds_read_b128 v[30:33], v137 offset:35840
	ds_read_b128 v[34:37], v137 offset:36864
	ds_read_b128 v[38:41], v137 offset:37888
	ds_read_b128 v[42:45], v137 offset:38912
	ds_read_b128 v[46:49], v137 offset:39936
	global_load_lds_dwordx4 v[66:67], off
	v_lshl_add_u64 v[66:67], v[230:231], 0, s[14:15]
	s_mov_b32 m0, s63
	s_nop 0
	global_load_lds_dwordx4 v[66:67], off
	s_waitcnt vmcnt(8)
	s_waitcnt lgkmcnt(0)
	s_barrier
	s_setprio 1
	v_mfma_f32_16x16x128_f8f6f4 v[126:129], v[2:9], v[10:17], v[126:129]
	v_mfma_f32_16x16x128_f8f6f4 v[122:125], v[18:25], v[10:17], v[122:125]
	v_mfma_f32_16x16x128_f8f6f4 v[106:109], v[18:25], v[26:33], v[106:109]
	v_mfma_f32_16x16x128_f8f6f4 v[110:113], v[2:9], v[26:33], v[110:113]
	v_mfma_f32_16x16x128_f8f6f4 v[94:97], v[2:9], v[34:41], v[132:135]
	v_mfma_f32_16x16x128_f8f6f4 v[90:93], v[18:25], v[34:41], v[214:217]
	v_mfma_f32_16x16x128_f8f6f4 v[74:77], v[18:25], v[42:49], v[222:225]
	v_mfma_f32_16x16x128_f8f6f4 v[78:81], v[2:9], v[42:49], v[218:221]
	v_mfma_f32_16x16x128_f8f6f4 v[118:121], v[138:145], v[10:17], v[118:121]
	v_mfma_f32_16x16x128_f8f6f4 v[114:117], v[146:153], v[10:17], v[114:117]
	v_mfma_f32_16x16x128_f8f6f4 v[98:101], v[146:153], v[26:33], v[98:101]
	v_mfma_f32_16x16x128_f8f6f4 v[102:105], v[138:145], v[26:33], v[102:105]
	v_mfma_f32_16x16x128_f8f6f4 v[86:89], v[138:145], v[34:41], v[170:173]
	v_mfma_f32_16x16x128_f8f6f4 v[82:85], v[146:153], v[34:41], v[174:177]
	v_mfma_f32_16x16x128_f8f6f4 v[66:69], v[146:153], v[42:49], v[182:185]
	v_mfma_f32_16x16x128_f8f6f4 v[70:73], v[138:145], v[42:49], v[178:181]
	s_setprio 0
	s_barrier
	s_add_i32 s2, s2, s59
	v_lshl_add_u64 v[10:11], v[232:233], 0, s[30:31]
	s_mov_b32 m0, s2
	ds_read_b128 v[34:37], v137 offset:49152
	ds_read_b128 v[38:41], v137 offset:50176
	ds_read_b128 v[154:157], v137 offset:51200
	ds_read_b128 v[158:161], v137 offset:52224
	ds_read_b128 v[162:165], v137 offset:53248
	ds_read_b128 v[166:169], v137 offset:54272
	ds_read_b128 v[170:173], v137 offset:55296
	ds_read_b128 v[174:177], v137 offset:56320
	global_load_lds_dwordx4 v[10:11], off
	v_lshl_add_u64 v[10:11], v[232:233], 0, s[24:25]
	s_add_i32 m0, s2, 0x2000
	s_add_i32 s2, s3, s59
	global_load_lds_dwordx4 v[10:11], off
	v_lshl_add_u64 v[10:11], v[232:233], 0, s[50:51]
	s_mov_b32 m0, s2
	s_nop 0
	global_load_lds_dwordx4 v[10:11], off
	v_lshl_add_u64 v[10:11], v[232:233], 0, s[4:5]
	s_add_i32 m0, s2, 0x2000
	s_nop 0
	global_load_lds_dwordx4 v[10:11], off
	v_lshl_add_u64 v[10:11], v[230:231], 0, s[30:31]
	s_mov_b32 m0, s66
	s_nop 0
	global_load_lds_dwordx4 v[10:11], off
	v_lshl_add_u64 v[10:11], v[230:231], 0, s[24:25]
	s_mov_b32 m0, s67
	s_nop 0
	global_load_lds_dwordx4 v[10:11], off
	s_waitcnt vmcnt(8)
	s_waitcnt lgkmcnt(0)
	s_barrier
	s_setprio 1
	v_mfma_f32_16x16x128_f8f6f4 v[62:65], v[2:9], v[34:41], v[62:65]
	v_mfma_f32_16x16x128_f8f6f4 v[58:61], v[18:25], v[34:41], v[58:61]
	v_mfma_f32_16x16x128_f8f6f4 v[42:45], v[18:25], v[154:161], v[190:193]
	v_mfma_f32_16x16x128_f8f6f4 v[46:49], v[2:9], v[154:161], v[186:189]
	v_mfma_f32_16x16x128_f8f6f4 v[30:33], v[2:9], v[162:169], v[206:209]
	v_mfma_f32_16x16x128_f8f6f4 v[26:29], v[18:25], v[162:169], v[210:213]
	v_mfma_f32_16x16x128_f8f6f4 v[10:13], v[18:25], v[170:177], v[246:249]
	v_mfma_f32_16x16x128_f8f6f4 v[14:17], v[2:9], v[170:177], v[242:245]
	v_mfma_f32_16x16x128_f8f6f4 v[54:57], v[138:145], v[34:41], v[54:57]
	v_mfma_f32_16x16x128_f8f6f4 v[50:53], v[146:153], v[34:41], v[50:53]
	v_mfma_f32_16x16x128_f8f6f4 v[34:37], v[146:153], v[154:161], v[198:201]
	v_mfma_f32_16x16x128_f8f6f4 v[38:41], v[138:145], v[154:161], v[234:237]
	v_mfma_f32_16x16x128_f8f6f4 v[22:25], v[138:145], v[162:169], v[202:205]
	v_mfma_f32_16x16x128_f8f6f4 v[18:21], v[146:153], v[162:169], v[194:197]
	v_mfma_f32_16x16x128_f8f6f4 v[2:5], v[146:153], v[170:177], v[226:229]
	v_mfma_f32_16x16x128_f8f6f4 v[6:9], v[138:145], v[170:177], v[238:241]
	s_setprio 0
	s_barrier
	s_add_i32 s97, s97, 2
	s_add_u32 s52, s52, 0x100
	s_addc_u32 s53, s53, 0
	s_add_u32 s95, s95, 0x100
	s_addc_u32 s96, s96, 0
	s_cmp_gt_u32 s97, 13
	s_cbranch_scc0 .LBB0_561
	s_and_b64 vcc, exec, s[40:41]
	s_cbranch_vccz .LBB0_564
	s_barrier
